# GEMM unit transition: accumulator re-zeroing with 64-bit moves (half the VALU instructions between units)
# speedup vs baseline: 1.0204x; 1.0021x over previous
; template <class Epi, class Sched, bool ALIGN_EPI = false, bool SP2 = false>
; __device__ __forceinline__ void gemm_phase(PG8_LAS unsigned char* lds, const Gemm g, const Sched& S, const Epi& E) {
;     ...
;         const bool has_next = S.next(ui + 1, nxt);
;         const char* nA = has_next ? (const char*)g.A + (size_t)nxt.pm * tstep : cA; const char* nB = has_next ? (const char*)g.Bt + (size_t)nxt.pn * tstep : cB;
;         for (int t = 0; t < nt; t += 2) {
;             const bool last = (t == nt - 2);
;             const char* a1 = cA + (size_t)(t + 1) * kstep;
;             const char* a2 = last ? nA : cA + (size_t)(t + 2) * kstep; const char* b2 = last ? nB : cB + (size_t)(t + 2) * kstep;
;             const char* a3 = a2 + kstep; const char* b3 = b2 + kstep;
;     ...
; #pragma unroll
;         for (int a = 0; a < 2; ++a)
; #pragma unroll
;             for (int b = 0; b < 2; ++b)
; #pragma unroll
;                 for (int m = 0; m < 4; ++m)
; #pragma unroll
;                     for (int n = 0; n < 2; ++n) acc[a][b][m][n] = (f32x4){0.f, 0.f, 0.f, 0.f};
;         cur = nxt; cA = nA; cB = nB; ++ui;
.LBB0_139:
	s_ashr_i32 s19, s18, 31
	s_lshl_b64 s[20:21], s[18:19], 19
	s_add_u32 s20, s56, s20
	s_addc_u32 s21, s57, s21
	s_and_b64 s[22:23], s[4:5], exec
	s_cselect_b32 s19, s21, s25
	s_cselect_b32 s48, s20, s24
	s_ashr_i32 s17, s16, 31
	s_lshl_b64 s[22:23], s[16:17], 19
	s_add_u32 s22, s30, s22
	s_addc_u32 s23, s31, s23
	s_and_b64 s[28:29], s[4:5], exec
	s_cselect_b32 s17, s23, s27
	s_cselect_b32 s49, s22, s26
	s_add_u32 s24, s24, 0x40080
	s_addc_u32 s25, s25, 0
	s_add_u32 s50, s26, 0x100
	v_mov_b32_e32 v0, 0
	s_addc_u32 s51, s27, 0
	s_mov_b32 s52, -2
	v_mov_b32_e32 v1, v0
	v_mov_b64_e32 v[2:3], 0
	v_mov_b64_e32 v[4:5], 0
	v_mov_b64_e32 v[6:7], 0
	v_mov_b64_e32 v[16:17], 0
	v_mov_b64_e32 v[18:19], 0
	v_mov_b64_e32 v[20:21], 0
	v_mov_b64_e32 v[22:23], 0
	v_mov_b64_e32 v[32:33], 0
	v_mov_b64_e32 v[34:35], 0
	v_mov_b64_e32 v[36:37], 0
	v_mov_b64_e32 v[38:39], 0
	v_mov_b64_e32 v[48:49], 0
	v_mov_b64_e32 v[50:51], 0
	v_mov_b64_e32 v[52:53], 0
	v_mov_b64_e32 v[54:55], 0
	v_mov_b64_e32 v[8:9], 0
	v_mov_b64_e32 v[10:11], 0
	v_mov_b32_e32 v12, v0
	s_waitcnt lgkmcnt(0)
	v_mov_b32_e32 v13, v0
	v_mov_b64_e32 v[14:15], 0
	v_mov_b64_e32 v[24:25], 0
	v_mov_b64_e32 v[26:27], 0
	v_mov_b64_e32 v[28:29], 0
	v_mov_b64_e32 v[30:31], 0
	v_mov_b64_e32 v[40:41], 0
	v_mov_b64_e32 v[42:43], 0
	v_mov_b64_e32 v[44:45], 0
	v_mov_b64_e32 v[46:47], 0
	v_mov_b64_e32 v[56:57], 0
	v_mov_b64_e32 v[58:59], 0
	v_mov_b64_e32 v[60:61], 0
	v_mov_b64_e32 v[62:63], 0
	v_mov_b64_e32 v[64:65], 0
	v_mov_b64_e32 v[66:67], 0
	v_mov_b64_e32 v[68:69], 0
	v_mov_b64_e32 v[70:71], 0
	v_mov_b64_e32 v[80:81], 0
	v_mov_b64_e32 v[82:83], 0
	v_mov_b64_e32 v[84:85], 0
	v_mov_b64_e32 v[86:87], 0
	v_mov_b64_e32 v[96:97], 0
	v_mov_b64_e32 v[98:99], 0
	v_mov_b64_e32 v[100:101], 0
	v_mov_b64_e32 v[102:103], 0
	v_mov_b64_e32 v[112:113], 0
	v_mov_b64_e32 v[114:115], 0
	v_mov_b64_e32 v[116:117], 0
	v_mov_b64_e32 v[118:119], 0
	v_mov_b64_e32 v[72:73], 0
	v_mov_b64_e32 v[74:75], 0
	v_mov_b64_e32 v[76:77], 0
	v_mov_b64_e32 v[78:79], 0
	v_mov_b64_e32 v[88:89], 0
	v_mov_b64_e32 v[90:91], 0
	v_mov_b64_e32 v[92:93], 0
	v_mov_b64_e32 v[94:95], 0
	v_mov_b64_e32 v[104:105], 0
	v_mov_b64_e32 v[106:107], 0
	v_mov_b64_e32 v[108:109], 0
	v_mov_b64_e32 v[110:111], 0
	v_mov_b64_e32 v[120:121], 0
	v_mov_b64_e32 v[122:123], 0
	v_mov_b64_e32 v[124:125], 0
	v_mov_b64_e32 v[126:127], 0

; template <class Epi, class Sched, bool ALIGN_EPI = false, bool SP2 = false>
; __device__ __forceinline__ void gemm_phase(PG8_LAS unsigned char* lds, const Gemm g, const Sched& S, const Epi& E) {
;     ...
;             const char* a1 = cA + (size_t)(t + 1) * kstep;
;             const char* a2 = last ? nA : cA + (size_t)(t + 2) * kstep; const char* b2 = last ? nB : cB + (size_t)(t + 2) * kstep;
;             const char* a3 = a2 + kstep; const char* b3 = b2 + kstep;
;     ...
; #pragma unroll
;         for (int a = 0; a < 2; ++a)
; #pragma unroll
;             for (int b = 0; b < 2; ++b)
; #pragma unroll
;                 for (int m = 0; m < 4; ++m)
; #pragma unroll
;                     for (int n = 0; n < 2; ++n) acc[a][b][m][n] = (f32x4){0.f, 0.f, 0.f, 0.f};
;         cur = nxt; cA = nA; cB = nB; ++ui;
.LBB0_314:
	s_add_u32 s26, s26, 0xb0080
	s_addc_u32 s27, s27, 0
	s_add_u32 s51, s28, 0x100
	v_mov_b32_e32 v0, 0
	s_addc_u32 s52, s29, 0
	s_mov_b32 s53, -2
	s_waitcnt lgkmcnt(0)
	v_mov_b32_e32 v1, v0
	v_mov_b64_e32 v[2:3], 0
	v_mov_b64_e32 v[4:5], 0
	v_mov_b64_e32 v[6:7], 0
	v_mov_b64_e32 v[16:17], 0
	v_mov_b64_e32 v[18:19], 0
	v_mov_b64_e32 v[20:21], 0
	v_mov_b64_e32 v[22:23], 0
	v_mov_b64_e32 v[32:33], 0
	v_mov_b64_e32 v[34:35], 0
	v_mov_b64_e32 v[36:37], 0
	v_mov_b64_e32 v[38:39], 0
	v_mov_b64_e32 v[48:49], 0
	v_mov_b64_e32 v[50:51], 0
	v_mov_b64_e32 v[52:53], 0
	v_mov_b64_e32 v[54:55], 0
	v_mov_b64_e32 v[8:9], 0
	v_mov_b64_e32 v[10:11], 0
	v_mov_b32_e32 v12, v0
	s_waitcnt lgkmcnt(0)
	v_mov_b32_e32 v13, v0
	v_mov_b64_e32 v[14:15], 0
	v_mov_b64_e32 v[24:25], 0
	v_mov_b64_e32 v[26:27], 0
	v_mov_b64_e32 v[28:29], 0
	v_mov_b64_e32 v[30:31], 0
	v_mov_b64_e32 v[40:41], 0
	v_mov_b64_e32 v[42:43], 0
	v_mov_b64_e32 v[44:45], 0
	v_mov_b64_e32 v[46:47], 0
	v_mov_b64_e32 v[56:57], 0
	v_mov_b64_e32 v[58:59], 0
	v_mov_b64_e32 v[60:61], 0
	v_mov_b64_e32 v[62:63], 0
	v_mov_b64_e32 v[64:65], 0
	v_mov_b64_e32 v[66:67], 0
	v_mov_b64_e32 v[68:69], 0
	v_mov_b64_e32 v[70:71], 0
	v_mov_b64_e32 v[80:81], 0
	v_mov_b64_e32 v[82:83], 0
	v_mov_b64_e32 v[84:85], 0
	v_mov_b64_e32 v[86:87], 0
	v_mov_b64_e32 v[96:97], 0
	v_mov_b64_e32 v[98:99], 0
	v_mov_b64_e32 v[100:101], 0
	v_mov_b64_e32 v[102:103], 0
	v_mov_b64_e32 v[112:113], 0
	v_mov_b64_e32 v[114:115], 0
	v_mov_b64_e32 v[116:117], 0
	v_mov_b64_e32 v[118:119], 0
	v_mov_b64_e32 v[72:73], 0
	v_mov_b64_e32 v[74:75], 0
	v_mov_b64_e32 v[76:77], 0
	v_mov_b64_e32 v[78:79], 0
	v_mov_b64_e32 v[88:89], 0
	v_mov_b64_e32 v[90:91], 0
	v_mov_b64_e32 v[92:93], 0
	v_mov_b64_e32 v[94:95], 0
	v_mov_b64_e32 v[104:105], 0
	v_mov_b64_e32 v[106:107], 0
	v_mov_b64_e32 v[108:109], 0
	v_mov_b64_e32 v[110:111], 0
	v_mov_b64_e32 v[120:121], 0
	v_mov_b64_e32 v[122:123], 0
	v_mov_b64_e32 v[124:125], 0
	v_mov_b64_e32 v[126:127], 0

; template <class Epi, class Sched, bool ALIGN_EPI = false, bool SP2 = false>
; __device__ __forceinline__ void gemm_phase(PG8_LAS unsigned char* lds, const Gemm g, const Sched& S, const Epi& E) {
;     ...
;         const bool has_next = S.next(ui + 1, nxt);
;         const char* nA = has_next ? (const char*)g.A + (size_t)nxt.pm * tstep : cA; const char* nB = has_next ? (const char*)g.Bt + (size_t)nxt.pn * tstep : cB;
;         for (int t = 0; t < nt; t += 2) {
;             const bool last = (t == nt - 2);
;             const char* a1 = cA + (size_t)(t + 1) * kstep;
;             const char* a2 = last ? nA : cA + (size_t)(t + 2) * kstep; const char* b2 = last ? nB : cB + (size_t)(t + 2) * kstep;
;             const char* a3 = a2 + kstep; const char* b3 = b2 + kstep;
;     ...
; #pragma unroll
;         for (int a = 0; a < 2; ++a)
; #pragma unroll
;             for (int b = 0; b < 2; ++b)
; #pragma unroll
;                 for (int m = 0; m < 4; ++m)
; #pragma unroll
;                     for (int n = 0; n < 2; ++n) acc[a][b][m][n] = (f32x4){0.f, 0.f, 0.f, 0.f};
;         cur = nxt; cA = nA; cB = nB; ++ui;
.LBB0_404:
	s_ashr_i32 s23, s22, 31
	s_lshl_b64 s[24:25], s[22:23], 19
	s_add_u32 s24, s56, s24
	s_addc_u32 s25, s57, s25
	s_and_b64 s[26:27], s[4:5], exec
	s_cselect_b32 s23, s25, s35
	s_cselect_b32 s52, s24, s34
	s_ashr_i32 s21, s20, 31
	s_lshl_b64 s[26:27], s[20:21], 19
	s_add_u32 s26, s17, s26
	s_addc_u32 s27, s19, s27
	s_and_b64 s[38:39], s[4:5], exec
	s_cselect_b32 s21, s27, s37
	s_cselect_b32 s53, s26, s36
	s_add_u32 s34, s34, 0x40080
	s_addc_u32 s35, s35, 0
	s_add_u32 s58, s36, 0x100
	v_mov_b32_e32 v0, 0
	s_addc_u32 s59, s37, 0
	s_mov_b32 s60, -2
	v_mov_b32_e32 v1, v0
	v_mov_b64_e32 v[2:3], 0
	v_mov_b64_e32 v[4:5], 0
	v_mov_b64_e32 v[6:7], 0
	v_mov_b64_e32 v[16:17], 0
	v_mov_b64_e32 v[18:19], 0
	v_mov_b64_e32 v[20:21], 0
	v_mov_b64_e32 v[22:23], 0
	v_mov_b64_e32 v[32:33], 0
	v_mov_b64_e32 v[34:35], 0
	v_mov_b64_e32 v[36:37], 0
	v_mov_b64_e32 v[38:39], 0
	v_mov_b64_e32 v[48:49], 0
	v_mov_b64_e32 v[50:51], 0
	v_mov_b64_e32 v[52:53], 0
	v_mov_b64_e32 v[54:55], 0
	v_mov_b64_e32 v[8:9], 0
	v_mov_b64_e32 v[10:11], 0
	v_mov_b64_e32 v[12:13], 0
	v_mov_b64_e32 v[14:15], 0
	v_mov_b64_e32 v[24:25], 0
	v_mov_b64_e32 v[26:27], 0
	v_mov_b64_e32 v[28:29], 0
	v_mov_b64_e32 v[30:31], 0
	v_mov_b64_e32 v[40:41], 0
	v_mov_b64_e32 v[42:43], 0
	v_mov_b64_e32 v[44:45], 0
	v_mov_b64_e32 v[46:47], 0
	v_mov_b64_e32 v[56:57], 0
	v_mov_b64_e32 v[58:59], 0
	v_mov_b64_e32 v[60:61], 0
	v_mov_b64_e32 v[62:63], 0
	v_mov_b64_e32 v[64:65], 0
	v_mov_b64_e32 v[66:67], 0
	v_mov_b64_e32 v[68:69], 0
	v_mov_b64_e32 v[70:71], 0
	v_mov_b64_e32 v[80:81], 0
	v_mov_b64_e32 v[82:83], 0
	v_mov_b64_e32 v[84:85], 0
	v_mov_b64_e32 v[86:87], 0
	v_mov_b64_e32 v[96:97], 0
	v_mov_b64_e32 v[98:99], 0
	v_mov_b64_e32 v[100:101], 0
	v_mov_b64_e32 v[102:103], 0
	v_mov_b64_e32 v[112:113], 0
	v_mov_b64_e32 v[114:115], 0
	v_mov_b64_e32 v[116:117], 0
	v_mov_b64_e32 v[118:119], 0
	v_mov_b64_e32 v[72:73], 0
	v_mov_b64_e32 v[74:75], 0
	v_mov_b64_e32 v[76:77], 0
	v_mov_b64_e32 v[78:79], 0
	v_mov_b64_e32 v[88:89], 0
	v_mov_b64_e32 v[90:91], 0
	v_mov_b64_e32 v[92:93], 0
	v_mov_b64_e32 v[94:95], 0
	v_mov_b64_e32 v[104:105], 0
	v_mov_b64_e32 v[106:107], 0
	v_mov_b64_e32 v[108:109], 0
	v_mov_b64_e32 v[110:111], 0
	v_mov_b64_e32 v[120:121], 0
	v_mov_b64_e32 v[122:123], 0
	v_mov_b64_e32 v[124:125], 0
	v_mov_b64_e32 v[126:127], 0

; template <class Epi, class Sched, bool ALIGN_EPI = false, bool SP2 = false>
; __device__ __forceinline__ void gemm_phase(PG8_LAS unsigned char* lds, const Gemm g, const Sched& S, const Epi& E) {
;     ...
;         const bool has_next = S.next(ui + 1, nxt);
;         const char* nA = has_next ? (const char*)g.A + (size_t)nxt.pm * tstep : cA; const char* nB = has_next ? (const char*)g.Bt + (size_t)nxt.pn * tstep : cB;
;         for (int t = 0; t < nt; t += 2) {
;             const bool last = (t == nt - 2);
;             const char* a1 = cA + (size_t)(t + 1) * kstep;
;             const char* a2 = last ? nA : cA + (size_t)(t + 2) * kstep; const char* b2 = last ? nB : cB + (size_t)(t + 2) * kstep;
;             const char* a3 = a2 + kstep; const char* b3 = b2 + kstep;
;     ...
; #pragma unroll
;         for (int a = 0; a < 2; ++a)
; #pragma unroll
;             for (int b = 0; b < 2; ++b)
; #pragma unroll
;                 for (int m = 0; m < 4; ++m)
; #pragma unroll
;                     for (int n = 0; n < 2; ++n) acc[a][b][m][n] = (f32x4){0.f, 0.f, 0.f, 0.f};
;         cur = nxt; cA = nA; cB = nB; ++ui;
.LBB0_1222:
	s_ashr_i32 s23, s22, 31
	s_lshl_b64 s[24:25], s[22:23], 19
	s_add_u32 s24, s42, s24
	s_addc_u32 s25, s43, s25
	s_and_b64 s[26:27], s[6:7], exec
	s_cselect_b32 s23, s25, s35
	s_cselect_b32 s29, s24, s34
	s_ashr_i32 s21, s20, 31
	s_lshl_b64 s[26:27], s[20:21], 19
	s_add_u32 s26, s33, s26
	s_addc_u32 s27, s40, s27
	s_and_b64 s[38:39], s[6:7], exec
	s_cselect_b32 s21, s27, s37
	s_cselect_b32 s58, s26, s36
	s_add_u32 s34, s34, 0x40080
	s_addc_u32 s35, s35, 0
	s_add_u32 s59, s36, 0x100
	v_mov_b32_e32 v0, 0
	s_addc_u32 s60, s37, 0
	s_mov_b32 s61, -2
	s_waitcnt lgkmcnt(0)
	v_mov_b32_e32 v1, v0
	v_mov_b32_e32 v2, v0
	v_mov_b32_e32 v3, v0
	v_mov_b32_e32 v4, v0
	v_mov_b32_e32 v5, v0
	v_mov_b32_e32 v6, v0
	v_mov_b32_e32 v7, v0
	s_waitcnt vmcnt(0)
	v_mov_b64_e32 v[16:17], 0
	v_mov_b64_e32 v[18:19], 0
	v_mov_b64_e32 v[20:21], 0
	v_mov_b64_e32 v[22:23], 0
	v_mov_b64_e32 v[32:33], 0
	v_mov_b64_e32 v[34:35], 0
	v_mov_b64_e32 v[36:37], 0
	v_mov_b64_e32 v[38:39], 0
	v_mov_b64_e32 v[48:49], 0
	v_mov_b64_e32 v[50:51], 0
	v_mov_b64_e32 v[52:53], 0
	v_mov_b64_e32 v[54:55], 0
	v_mov_b64_e32 v[8:9], 0
	v_mov_b64_e32 v[10:11], 0
	v_mov_b64_e32 v[12:13], 0
	v_mov_b64_e32 v[14:15], 0
	v_mov_b64_e32 v[24:25], 0
	v_mov_b64_e32 v[26:27], 0
	v_mov_b64_e32 v[28:29], 0
	v_mov_b64_e32 v[30:31], 0
	v_mov_b64_e32 v[40:41], 0
	v_mov_b64_e32 v[42:43], 0
	v_mov_b64_e32 v[44:45], 0
	v_mov_b64_e32 v[46:47], 0
	v_mov_b64_e32 v[56:57], 0
	v_mov_b64_e32 v[58:59], 0
	v_mov_b64_e32 v[60:61], 0
	v_mov_b64_e32 v[62:63], 0
	v_mov_b64_e32 v[64:65], 0
	v_mov_b64_e32 v[66:67], 0
	v_mov_b64_e32 v[68:69], 0
	v_mov_b64_e32 v[70:71], 0
	v_mov_b64_e32 v[80:81], 0
	v_mov_b64_e32 v[82:83], 0
	v_mov_b64_e32 v[84:85], 0
	v_mov_b64_e32 v[86:87], 0
	v_mov_b64_e32 v[96:97], 0
	v_mov_b64_e32 v[98:99], 0
	v_mov_b64_e32 v[100:101], 0
	v_mov_b64_e32 v[102:103], 0
	v_mov_b64_e32 v[112:113], 0
	v_mov_b64_e32 v[114:115], 0
	v_mov_b64_e32 v[116:117], 0
	v_mov_b64_e32 v[118:119], 0
	v_mov_b64_e32 v[72:73], 0
	v_mov_b64_e32 v[74:75], 0
	v_mov_b64_e32 v[76:77], 0
	v_mov_b64_e32 v[78:79], 0
	v_mov_b64_e32 v[88:89], 0
	v_mov_b64_e32 v[90:91], 0
	v_mov_b64_e32 v[92:93], 0
	v_mov_b64_e32 v[94:95], 0
	v_mov_b64_e32 v[104:105], 0
	v_mov_b64_e32 v[106:107], 0
	v_mov_b64_e32 v[108:109], 0
	v_mov_b64_e32 v[110:111], 0
	v_mov_b64_e32 v[120:121], 0
	v_mov_b64_e32 v[122:123], 0
	v_mov_b64_e32 v[124:125], 0
	v_mov_b64_e32 v[126:127], 0

; template <class Epi, class Sched, bool ALIGN_EPI = false, bool SP2 = false>
; __device__ __forceinline__ void gemm_phase(PG8_LAS unsigned char* lds, const Gemm g, const Sched& S, const Epi& E) {
;     ...
;         const bool has_next = S.next(ui + 1, nxt);
;         const char* nA = has_next ? (const char*)g.A + (size_t)nxt.pm * tstep : cA; const char* nB = has_next ? (const char*)g.Bt + (size_t)nxt.pn * tstep : cB;
;         for (int t = 0; t < nt; t += 2) {
;             const bool last = (t == nt - 2);
;             const char* a1 = cA + (size_t)(t + 1) * kstep;
;             const char* a2 = last ? nA : cA + (size_t)(t + 2) * kstep; const char* b2 = last ? nB : cB + (size_t)(t + 2) * kstep;
;             const char* a3 = a2 + kstep; const char* b3 = b2 + kstep;
;     ...
; #pragma unroll
;         for (int a = 0; a < 2; ++a)
; #pragma unroll
;             for (int b = 0; b < 2; ++b)
; #pragma unroll
;                 for (int m = 0; m < 4; ++m)
; #pragma unroll
;                     for (int n = 0; n < 2; ++n) acc[a][b][m][n] = (f32x4){0.f, 0.f, 0.f, 0.f};
;         cur = nxt; cA = nA; cB = nB; ++ui;
.LBB0_1309:
	s_ashr_i32 s21, s20, 31
	s_lshl_b64 s[22:23], s[20:21], 19
	s_add_u32 s22, s56, s22
	s_addc_u32 s23, s57, s23
	s_and_b64 s[24:25], s[4:5], exec
	s_cselect_b32 s21, s23, s27
	s_cselect_b32 s50, s22, s26
	s_ashr_i32 s19, s18, 31
	s_lshl_b64 s[24:25], s[18:19], 19
	s_add_u32 s24, s33, s24
	s_addc_u32 s25, s34, s25
	s_and_b64 s[30:31], s[4:5], exec
	s_cselect_b32 s19, s25, s29
	s_cselect_b32 s51, s24, s28
	s_add_u32 s26, s26, 0x40080
	s_addc_u32 s27, s27, 0
	s_add_u32 s52, s28, 0x100
	v_mov_b32_e32 v0, 0
	s_addc_u32 s53, s29, 0
	s_mov_b32 s58, -2
	v_mov_b32_e32 v1, v0
	v_mov_b32_e32 v2, v0
	v_mov_b32_e32 v3, v0
	v_mov_b32_e32 v4, v0
	v_mov_b32_e32 v5, v0
	v_mov_b32_e32 v6, v0
	v_mov_b32_e32 v7, v0
	s_waitcnt vmcnt(0)
	v_mov_b64_e32 v[16:17], 0
	v_mov_b64_e32 v[18:19], 0
	v_mov_b64_e32 v[20:21], 0
	v_mov_b64_e32 v[22:23], 0
	v_mov_b64_e32 v[32:33], 0
	v_mov_b64_e32 v[34:35], 0
	v_mov_b64_e32 v[36:37], 0
	v_mov_b64_e32 v[38:39], 0
	v_mov_b64_e32 v[48:49], 0
	v_mov_b64_e32 v[50:51], 0
	v_mov_b64_e32 v[52:53], 0
	v_mov_b64_e32 v[54:55], 0
	v_mov_b64_e32 v[8:9], 0
	v_mov_b64_e32 v[10:11], 0
	v_mov_b64_e32 v[12:13], 0
	v_mov_b64_e32 v[14:15], 0
	v_mov_b64_e32 v[24:25], 0
	v_mov_b64_e32 v[26:27], 0
	v_mov_b64_e32 v[28:29], 0
	v_mov_b64_e32 v[30:31], 0
	v_mov_b64_e32 v[40:41], 0
	v_mov_b64_e32 v[42:43], 0
	v_mov_b64_e32 v[44:45], 0
	v_mov_b64_e32 v[46:47], 0
	v_mov_b64_e32 v[56:57], 0
	v_mov_b64_e32 v[58:59], 0
	v_mov_b64_e32 v[60:61], 0
	v_mov_b64_e32 v[62:63], 0
	v_mov_b64_e32 v[64:65], 0
	v_mov_b64_e32 v[66:67], 0
	v_mov_b64_e32 v[68:69], 0
	v_mov_b64_e32 v[70:71], 0
	v_mov_b64_e32 v[80:81], 0
	v_mov_b64_e32 v[82:83], 0
	v_mov_b64_e32 v[84:85], 0
	v_mov_b64_e32 v[86:87], 0
	v_mov_b64_e32 v[96:97], 0
	v_mov_b64_e32 v[98:99], 0
	v_mov_b64_e32 v[100:101], 0
	v_mov_b64_e32 v[102:103], 0
	v_mov_b64_e32 v[112:113], 0
	v_mov_b64_e32 v[114:115], 0
	v_mov_b64_e32 v[116:117], 0
	v_mov_b64_e32 v[118:119], 0
	v_mov_b64_e32 v[72:73], 0
	v_mov_b64_e32 v[74:75], 0
	v_mov_b64_e32 v[76:77], 0
	v_mov_b64_e32 v[78:79], 0
	v_mov_b64_e32 v[88:89], 0
	v_mov_b64_e32 v[90:91], 0
	v_mov_b64_e32 v[92:93], 0
	v_mov_b64_e32 v[94:95], 0
	v_mov_b64_e32 v[104:105], 0
	v_mov_b64_e32 v[106:107], 0
	v_mov_b64_e32 v[108:109], 0
	v_mov_b64_e32 v[110:111], 0
	v_mov_b64_e32 v[120:121], 0
	v_mov_b64_e32 v[122:123], 0
	v_mov_b64_e32 v[124:125], 0
	v_mov_b64_e32 v[126:127], 0

; template <class Epi, class Sched, bool ALIGN_EPI = false, bool SP2 = false>
; __device__ __forceinline__ void gemm_phase(PG8_LAS unsigned char* lds, const Gemm g, const Sched& S, const Epi& E) {
;     ...
;             const char* a1 = cA + (size_t)(t + 1) * kstep;
;             const char* a2 = last ? nA : cA + (size_t)(t + 2) * kstep; const char* b2 = last ? nB : cB + (size_t)(t + 2) * kstep;
;             const char* a3 = a2 + kstep; const char* b3 = b2 + kstep;
;     ...
; #pragma unroll
;         for (int a = 0; a < 2; ++a)
; #pragma unroll
;             for (int b = 0; b < 2; ++b)
; #pragma unroll
;                 for (int m = 0; m < 4; ++m)
; #pragma unroll
;                     for (int n = 0; n < 2; ++n) acc[a][b][m][n] = (f32x4){0.f, 0.f, 0.f, 0.f};
;         cur = nxt; cA = nA; cB = nB; ++ui;
.LBB0_1394:
	s_add_u32 s6, s36, 0xb0080
	s_addc_u32 s7, s37, 0
	s_add_u32 s60, s34, 0x100
	v_mov_b32_e32 v0, 0
	s_addc_u32 s61, s35, 0
	s_mov_b32 s62, -2
	v_mov_b32_e32 v1, v0
	v_mov_b32_e32 v2, v0
	v_mov_b32_e32 v3, v0
	v_mov_b32_e32 v4, v0
	v_mov_b32_e32 v5, v0
	v_mov_b32_e32 v6, v0
	v_mov_b32_e32 v7, v0
	s_waitcnt vmcnt(0)
	v_mov_b64_e32 v[12:13], 0
	v_mov_b64_e32 v[14:15], 0
	v_mov_b64_e32 v[20:21], 0
	v_mov_b64_e32 v[22:23], 0
	v_mov_b64_e32 v[28:29], 0
	v_mov_b64_e32 v[30:31], 0
	v_mov_b64_e32 v[36:37], 0
	v_mov_b64_e32 v[38:39], 0
	v_mov_b64_e32 v[48:49], 0
	v_mov_b64_e32 v[50:51], 0
	v_mov_b64_e32 v[52:53], 0
	v_mov_b64_e32 v[54:55], 0
	v_mov_b64_e32 v[8:9], 0
	v_mov_b64_e32 v[10:11], 0
	v_mov_b64_e32 v[16:17], 0
	v_mov_b64_e32 v[18:19], 0
	v_mov_b64_e32 v[24:25], 0
	v_mov_b64_e32 v[26:27], 0
	v_mov_b64_e32 v[32:33], 0
	v_mov_b64_e32 v[34:35], 0
	v_mov_b64_e32 v[40:41], 0
	v_mov_b64_e32 v[42:43], 0
	v_mov_b64_e32 v[44:45], 0
	v_mov_b64_e32 v[46:47], 0
	v_mov_b64_e32 v[56:57], 0
	v_mov_b64_e32 v[58:59], 0
	v_mov_b64_e32 v[60:61], 0
	v_mov_b64_e32 v[62:63], 0
	v_mov_b64_e32 v[64:65], 0
	v_mov_b64_e32 v[66:67], 0
	v_mov_b64_e32 v[68:69], 0
	v_mov_b64_e32 v[70:71], 0
	v_mov_b64_e32 v[76:77], 0
	v_mov_b64_e32 v[78:79], 0
	v_mov_b64_e32 v[84:85], 0
	v_mov_b64_e32 v[86:87], 0
	v_mov_b64_e32 v[92:93], 0
	v_mov_b64_e32 v[94:95], 0
	v_mov_b64_e32 v[100:101], 0
	v_mov_b64_e32 v[102:103], 0
	v_mov_b64_e32 v[112:113], 0
	v_mov_b64_e32 v[114:115], 0
	v_mov_b64_e32 v[116:117], 0
	v_mov_b64_e32 v[118:119], 0
	v_mov_b64_e32 v[72:73], 0
	v_mov_b64_e32 v[74:75], 0
	v_mov_b64_e32 v[80:81], 0
	v_mov_b64_e32 v[82:83], 0
	v_mov_b64_e32 v[88:89], 0
	v_mov_b64_e32 v[90:91], 0
	v_mov_b64_e32 v[96:97], 0
	v_mov_b64_e32 v[98:99], 0
	v_mov_b64_e32 v[104:105], 0
	v_mov_b64_e32 v[106:107], 0
	v_mov_b64_e32 v[108:109], 0
	v_mov_b64_e32 v[110:111], 0
	v_mov_b64_e32 v[120:121], 0
	v_mov_b64_e32 v[122:123], 0
	v_mov_b64_e32 v[124:125], 0
	v_mov_b64_e32 v[126:127], 0
